# k39 + 64-byte alignment of the modulation, E-GEMM, Y-GEMM and GLU K-loop heads
# speedup vs baseline: 1.0061x; 1.0061x over previous
; #define PG8_STAGE(bufoff, gbase, voff) do { _Pragma("unroll") for (int _i = 0; _i < 2; ++_i) \
;         __builtin_amdgcn_global_load_lds((const unsigned*)((const char*)(gbase) + (voff)[_i]), (LAS unsigned*)(lds + (bufoff) + ldsw + _i * 8192), 16, 0, 0); } while (0)
; #define PG8_WAIT_V(n) asm volatile("s_waitcnt vmcnt(" #n ")" ::: "memory")
; #define PG8_BAR __builtin_amdgcn_s_barrier()
; template <class Epi, bool ALIGN_EPI>
; __device__ __forceinline__ void gemm_phase(LAS unsigned char* lds, const Gemm g, const Order& S, const Epi& E, const int wave_id) {
;     ...
;     f32x4 acc[2][2][4][2];
; #pragma unroll
;     for (int a = 0; a < 2; ++a)
; #pragma unroll
;         for (int b = 0; b < 2; ++b)
; #pragma unroll
;             for (int m = 0; m < 4; ++m)
; #pragma unroll
;                 for (int n = 0; n < 2; ++n) acc[a][b][m][n] = (f32x4){0.f, 0.f, 0.f, 0.f};
;     bf16x8 At[4][2], B0[2][2], B1[2][2];
;     const char* cA = (const char*)g.A + (size_t)cur.z * g.sAz + (size_t)cur.pm * 2 * hstepA + (size_t)cur.k0 * 2; const char* cB = (const char*)g.Bt + (size_t)cur.z * g.sBz + (size_t)cur.pn * 2 * hstepB + (size_t)cur.k0 * 2;
;     PG8_STAGE(PG8_SB(0, 0), cB, voffB); PG8_STAGE(PG8_SB(0, 1), cB + hstepB, voffB); PG8_STAGE(PG8_SA(0, 0), cA, voffA); PG8_STAGE(PG8_SA(0, 1), cA + hstepA, voffA);
;     if (wr == 1) PG8_BAR;
;     PG8_WAIT_V(2); PG8_BAR;
;     PG8_STAGE(PG8_SB(1, 0), cB + kstep, voffB); PG8_STAGE(PG8_SA(1, 0), cA + kstep, voffA); PG8_STAGE(PG8_SB(1, 1), cB + hstepB + kstep, voffB);
;     PG8_WAIT_V(6); PG8_BAR;
;     for (;;) {
;         const bool has_next = S.next(ui + 1, nxt);
;         const char* nA = has_next ? (const char*)g.A + (size_t)nxt.z * g.sAz + (size_t)nxt.pm * 2 * hstepA + (size_t)nxt.k0 * 2 : cA;
;         const char* nB = has_next ? (const char*)g.Bt + (size_t)nxt.z * g.sBz + (size_t)nxt.pn * 2 * hstepB + (size_t)nxt.k0 * 2 : cB;
;         const int nt = cur.nt;
;         for (int t = 0; t < nt; t += 2) {
.LBB0_226:
	s_add_u32 s17, s20, 0x100
	v_mov_b32_e32 v0, 0
	s_addc_u32 s19, s21, 0
	s_mov_b32 s52, -2
	s_mov_b64 s[20:21], 0
	v_mov_b32_e32 v1, v0
	v_mov_b32_e32 v2, v0
	v_mov_b32_e32 v3, v0
	v_mov_b32_e32 v4, v0
	v_mov_b32_e32 v5, v0
	v_mov_b32_e32 v6, v0
	v_mov_b32_e32 v7, v0
	v_mov_b32_e32 v16, v0
	v_mov_b32_e32 v17, v0
	v_mov_b32_e32 v18, v0
	v_mov_b32_e32 v19, v0
	v_mov_b32_e32 v20, v0
	v_mov_b32_e32 v21, v0
	v_mov_b32_e32 v22, v0
	v_mov_b32_e32 v23, v0
	v_mov_b32_e32 v32, v0
	v_mov_b32_e32 v33, v0
	v_mov_b32_e32 v34, v0
	v_mov_b32_e32 v35, v0
	v_mov_b32_e32 v36, v0
	v_mov_b32_e32 v37, v0
	v_mov_b32_e32 v38, v0
	v_mov_b32_e32 v39, v0
	v_mov_b32_e32 v48, v0
	v_mov_b32_e32 v49, v0
	v_mov_b32_e32 v50, v0
	v_mov_b32_e32 v51, v0
	v_mov_b32_e32 v52, v0
	v_mov_b32_e32 v53, v0
	v_mov_b32_e32 v54, v0
	v_mov_b32_e32 v55, v0
	v_mov_b32_e32 v8, v0
	v_mov_b32_e32 v9, v0
	v_mov_b32_e32 v10, v0
	v_mov_b32_e32 v11, v0
	v_mov_b32_e32 v12, v0
	v_mov_b32_e32 v13, v0
	v_mov_b32_e32 v14, v0
	v_mov_b32_e32 v15, v0
	v_mov_b32_e32 v24, v0
	v_mov_b32_e32 v25, v0
	v_mov_b32_e32 v26, v0
	v_mov_b32_e32 v27, v0
	v_mov_b32_e32 v28, v0
	v_mov_b32_e32 v29, v0
	v_mov_b32_e32 v30, v0
	v_mov_b32_e32 v31, v0
	v_mov_b32_e32 v40, v0
	v_mov_b32_e32 v41, v0
	v_mov_b32_e32 v42, v0
	v_mov_b32_e32 v43, v0
	v_mov_b32_e32 v44, v0
	v_mov_b32_e32 v45, v0
	v_mov_b32_e32 v46, v0
	v_mov_b32_e32 v47, v0
	v_mov_b32_e32 v56, v0
	v_mov_b32_e32 v57, v0
	v_mov_b32_e32 v58, v0
	v_mov_b32_e32 v59, v0
	v_mov_b32_e32 v60, v0
	v_mov_b32_e32 v61, v0
	v_mov_b32_e32 v62, v0
	v_mov_b32_e32 v63, v0
	v_mov_b32_e32 v64, v0
	v_mov_b32_e32 v65, v0
	v_mov_b32_e32 v66, v0
	v_mov_b32_e32 v67, v0
	v_mov_b32_e32 v68, v0
	v_mov_b32_e32 v69, v0
	v_mov_b32_e32 v70, v0
	v_mov_b32_e32 v71, v0
	v_mov_b32_e32 v80, v0
	v_mov_b32_e32 v81, v0
	v_mov_b32_e32 v82, v0
	v_mov_b32_e32 v83, v0
	v_mov_b32_e32 v84, v0
	v_mov_b32_e32 v85, v0
	v_mov_b32_e32 v86, v0
	v_mov_b32_e32 v87, v0
	v_mov_b32_e32 v96, v0
	v_mov_b32_e32 v97, v0
	v_mov_b32_e32 v98, v0
	v_mov_b32_e32 v99, v0
	v_mov_b32_e32 v100, v0
	v_mov_b32_e32 v101, v0
	v_mov_b32_e32 v102, v0
	v_mov_b32_e32 v103, v0
	v_mov_b32_e32 v112, v0
	v_mov_b32_e32 v113, v0
	v_mov_b32_e32 v114, v0
	v_mov_b32_e32 v115, v0
	v_mov_b32_e32 v116, v0
	v_mov_b32_e32 v117, v0
	v_mov_b32_e32 v118, v0
	v_mov_b32_e32 v119, v0
	v_mov_b32_e32 v72, v0
	v_mov_b32_e32 v73, v0
	v_mov_b32_e32 v74, v0
	v_mov_b32_e32 v75, v0
	v_mov_b32_e32 v76, v0
	v_mov_b32_e32 v77, v0
	v_mov_b32_e32 v78, v0
	v_mov_b32_e32 v79, v0
	v_mov_b32_e32 v88, v0
	v_mov_b32_e32 v89, v0
	v_mov_b32_e32 v90, v0
	v_mov_b32_e32 v91, v0
	v_mov_b32_e32 v92, v0
	v_mov_b32_e32 v93, v0
	v_mov_b32_e32 v94, v0
	v_mov_b32_e32 v95, v0
	v_mov_b32_e32 v104, v0
	v_mov_b32_e32 v105, v0
	v_mov_b32_e32 v106, v0
	v_mov_b32_e32 v107, v0
	v_mov_b32_e32 v108, v0
	v_mov_b32_e32 v109, v0
	v_mov_b32_e32 v110, v0
	v_mov_b32_e32 v111, v0
	v_mov_b32_e32 v120, v0
	v_mov_b32_e32 v121, v0
	v_mov_b32_e32 v122, v0
	v_mov_b32_e32 v123, v0
	v_mov_b32_e32 v124, v0
	v_mov_b32_e32 v125, v0
	v_mov_b32_e32 v126, v0
	v_mov_b32_e32 v127, v0
	.p2align 6

; #define PG8_STAGE(bufoff, gbase, voff) do { _Pragma("unroll") for (int _i = 0; _i < 2; ++_i) \
;         __builtin_amdgcn_global_load_lds((const unsigned*)((const char*)(gbase) + (voff)[_i]), (LAS unsigned*)(lds + (bufoff) + ldsw + _i * 8192), 16, 0, 0); } while (0)
; #define PG8_WAIT_V(n) asm volatile("s_waitcnt vmcnt(" #n ")" ::: "memory")
; #define PG8_BAR __builtin_amdgcn_s_barrier()
; template <class Epi, bool ALIGN_EPI>
; __device__ __forceinline__ void gemm_phase(LAS unsigned char* lds, const Gemm g, const Order& S, const Epi& E, const int wave_id) {
;     ...
;     PG8_WAIT_V(2); PG8_BAR;
;     PG8_STAGE(PG8_SB(1, 0), cB + kstep, voffB); PG8_STAGE(PG8_SA(1, 0), cA + kstep, voffA); PG8_STAGE(PG8_SB(1, 1), cB + hstepB + kstep, voffB);
;     PG8_WAIT_V(6); PG8_BAR;
;     for (;;) {
;         const bool has_next = S.next(ui + 1, nxt);
;         const char* nA = has_next ? (const char*)g.A + (size_t)nxt.z * g.sAz + (size_t)nxt.pm * 2 * hstepA + (size_t)nxt.k0 * 2 : cA;
;         const char* nB = has_next ? (const char*)g.Bt + (size_t)nxt.z * g.sBz + (size_t)nxt.pn * 2 * hstepB + (size_t)nxt.k0 * 2 : cB;
;         const int nt = cur.nt;
;         for (int t = 0; t < nt; t += 2) {
;     __device__ __forceinline__ void fused(const Acc& acc, const Unit& u, int wr, int wc, int fr, int fq, LAS unsigned char* lds, int wid, int lane) const {
;     ...
;             const float ar = apow[((g * 17 + 16) * 64 + p) * 2], aim = apow[((g * 17 + 16) * 64 + p) * 2 + 1];
.LBB0_917:
	v_lshl_add_u64 v[2:3], s[2:3], 0, v[160:161]
	v_mov_b32_e32 v67, v161
	v_lshl_add_u64 v[4:5], s[2:3], 0, v[66:67]
	v_mov_b32_e32 v71, v161
	s_add_i32 m0, s22, 0x18000
	v_lshl_add_u64 v[2:3], v[2:3], 0, s[82:83]
	v_lshl_add_u64 v[6:7], s[0:1], 0, v[70:71]
	v_mov_b32_e32 v69, v161
	s_and_b32 s28, s19, 3
	s_waitcnt vmcnt(2)
	s_barrier
	global_load_lds_dwordx4 v[2:3], off
	v_lshl_add_u64 v[2:3], v[4:5], 0, s[82:83]
	s_add_i32 m0, s22, 0x1a000
	s_add_i32 s29, s22, 0x8000
	s_add_i32 s30, s22, 0xa000
	v_lshl_add_u64 v[8:9], s[0:1], 0, v[68:69]
	global_load_lds_dwordx4 v[2:3], off
	v_lshl_add_u64 v[2:3], v[6:7], 0, s[82:83]
	s_mov_b32 m0, s29
	s_add_u32 s4, s2, 0x10080
	global_load_lds_dwordx4 v[2:3], off
	v_lshl_add_u64 v[2:3], v[8:9], 0, s[82:83]
	s_mov_b32 m0, s30
	s_addc_u32 s5, s3, 0
	s_add_i32 s31, s22, 0x1c000
	global_load_lds_dwordx4 v[2:3], off
	v_lshl_add_u64 v[2:3], s[4:5], 0, v[160:161]
	s_mov_b32 m0, s31
	s_add_i32 s34, s22, 0x1e000
	global_load_lds_dwordx4 v[2:3], off
	v_lshl_add_u64 v[2:3], s[4:5], 0, v[66:67]
	s_mov_b32 m0, s34
	v_and_b32_e32 v65, 15, v64
	global_load_lds_dwordx4 v[2:3], off
	v_and_b32_e32 v1, 48, v64
	v_and_b32_e32 v0, 0xfffffc00, v0
	v_lshlrev_b32_e32 v3, 2, v64
	v_lshl_or_b32 v1, v65, 6, v1
	v_lshl_add_u32 v2, s20, 13, v0
	v_and_b32_e32 v3, 32, v3
	v_lshl_add_u32 v0, s28, 12, v0
	s_waitcnt vmcnt(6)
	v_bitop3_b32 v2, v1, v2, v3 bitop3:0xde
	v_bitop3_b32 v72, v1, v0, v3 bitop3:0xde
	v_mov_b32_e32 v0, 0
	s_mov_b32 s35, 0
	s_mov_b64 s[4:5], -1
	s_mov_b64 s[6:7], 0
	v_add_u32_e32 v73, 0, v2
	v_mov_b32_e32 v1, v0
	v_mov_b32_e32 v2, v0
	v_mov_b32_e32 v3, v0
	v_mov_b32_e32 v4, v0
	v_mov_b32_e32 v5, v0
	v_mov_b32_e32 v6, v0
	v_mov_b32_e32 v7, v0
	v_mov_b32_e32 v8, v0
	v_mov_b32_e32 v9, v0
	v_mov_b32_e32 v10, v0
	v_mov_b32_e32 v11, v0
	v_mov_b32_e32 v12, v0
	v_mov_b32_e32 v13, v0
	v_mov_b32_e32 v14, v0
	v_mov_b32_e32 v15, v0
	v_mov_b32_e32 v16, v0
	v_mov_b32_e32 v17, v0
	v_mov_b32_e32 v18, v0
	v_mov_b32_e32 v19, v0
	v_mov_b32_e32 v20, v0
	v_mov_b32_e32 v21, v0
	v_mov_b32_e32 v22, v0
	v_mov_b32_e32 v23, v0
	v_mov_b32_e32 v24, v0
	v_mov_b32_e32 v25, v0
	v_mov_b32_e32 v26, v0
	v_mov_b32_e32 v27, v0
	v_mov_b32_e32 v28, v0
	v_mov_b32_e32 v29, v0
	v_mov_b32_e32 v30, v0
	v_mov_b32_e32 v31, v0
	v_mov_b32_e32 v32, v0
	v_mov_b32_e32 v33, v0
	v_mov_b32_e32 v34, v0
	v_mov_b32_e32 v35, v0
	v_mov_b32_e32 v36, v0
	v_mov_b32_e32 v37, v0
	v_mov_b32_e32 v38, v0
	v_mov_b32_e32 v39, v0
	v_mov_b32_e32 v40, v0
	v_mov_b32_e32 v41, v0
	v_mov_b32_e32 v42, v0
	v_mov_b32_e32 v43, v0
	v_mov_b32_e32 v44, v0
	v_mov_b32_e32 v45, v0
	v_mov_b32_e32 v46, v0
	v_mov_b32_e32 v47, v0
	v_mov_b32_e32 v48, v0
	v_mov_b32_e32 v49, v0
	v_mov_b32_e32 v50, v0
	v_mov_b32_e32 v51, v0
	v_mov_b32_e32 v52, v0
	v_mov_b32_e32 v53, v0
	v_mov_b32_e32 v54, v0
	v_mov_b32_e32 v55, v0
	v_mov_b32_e32 v56, v0
	v_mov_b32_e32 v57, v0
	v_mov_b32_e32 v58, v0
	v_mov_b32_e32 v59, v0
	v_mov_b32_e32 v60, v0
	v_mov_b32_e32 v61, v0
	v_mov_b32_e32 v62, v0
	v_mov_b32_e32 v63, v0
	s_barrier
	s_mul_i32 s8, s74, 0x440
	v_add_u32_e32 v242, s8, v64
	v_lshl_add_u32 v242, v242, 1, v204
	v_ashrrev_i32_e32 v243, 31, v242
	v_readlane_b32 s8, v253, 13
	v_readlane_b32 s9, v253, 14
	s_mul_i32 s36, s96, 0x22000
	s_mul_hi_u32 s37, s96, 0x22000
	s_nop 1
	s_add_u32 s8, s8, s36
	s_addc_u32 s9, s9, s37
	s_add_u32 s8, s8, 0x400000
	s_addc_u32 s9, s9, 0
	v_lshl_add_u64 v[242:243], v[242:243], 2, s[8:9]
	global_load_dwordx2 v[240:241], v[242:243], off
	.p2align 6

; #define PG8_STAGE(bufoff, gbase, voff) do { _Pragma("unroll") for (int _i = 0; _i < 2; ++_i) \
;         __builtin_amdgcn_global_load_lds((const unsigned*)((const char*)(gbase) + (voff)[_i]), (LAS unsigned*)(lds + (bufoff) + ldsw + _i * 8192), 16, 0, 0); } while (0)
; #define PG8_WAIT_V(n) asm volatile("s_waitcnt vmcnt(" #n ")" ::: "memory")
; #define PG8_BAR __builtin_amdgcn_s_barrier()
; template <class Epi, bool ALIGN_EPI>
; __device__ __forceinline__ void gemm_phase(LAS unsigned char* lds, const Gemm g, const Order& S, const Epi& E, const int wave_id) {
;     ...
;     PG8_STAGE(PG8_SB(1, 0), cB + kstep, voffB); PG8_STAGE(PG8_SA(1, 0), cA + kstep, voffA); PG8_STAGE(PG8_SB(1, 1), cB + hstepB + kstep, voffB);
;     PG8_WAIT_V(6); PG8_BAR;
;     for (;;) {
;         const bool has_next = S.next(ui + 1, nxt);
;         const char* nA = has_next ? (const char*)g.A + (size_t)nxt.z * g.sAz + (size_t)nxt.pm * 2 * hstepA + (size_t)nxt.k0 * 2 : cA;
;         const char* nB = has_next ? (const char*)g.Bt + (size_t)nxt.z * g.sBz + (size_t)nxt.pn * 2 * hstepB + (size_t)nxt.k0 * 2 : cB;
;         const int nt = cur.nt;
;         for (int t = 0; t < nt; t += 2) {
; __global__ void __launch_bounds__(512, 2) hybrid_fwd(Params P) {
;     ...
;                 pg8::Gemm g{ZUT, BTY + (size_t)l * 16 * 256 * KY, KY, KY, KY, (size_t)NCHUNK * KY * 2, (size_t)256 * KY * 2}; pg8::Order S; S.init(4, 1, 16, 64, bid, KY / 64);
;                 EpiY E{Zb};
;                 pg8::gemm_phase<EpiY, true>(ldsl, g, S, E, wave);
.LBB0_1074:
	v_ashrrev_i32_e32 v16, 6, v135
	v_lshlrev_b32_e32 v18, 10, v16
	s_lshl_b32 s18, s4, 6
	v_lshl_add_u32 v18, s4, 13, v18
	v_readlane_b32 s4, v253, 62
	s_lshl_b32 s4, s4, 5
	s_and_b32 s20, s4, 0x60
	s_add_i32 m0, s15, 0x18000
	v_lshl_add_u64 v[6:7], v[6:7], 0, s[82:83]
	s_lshr_b32 s4, s20, 3
	s_waitcnt vmcnt(2)
	s_barrier
	global_load_lds_dwordx4 v[6:7], off
	v_lshl_add_u64 v[4:5], v[4:5], 0, s[82:83]
	s_add_i32 m0, s15, 0x1a000
	s_add_i32 s21, s15, 0x8000
	s_add_i32 s22, s15, 0xa000
	global_load_lds_dwordx4 v[4:5], off
	v_lshl_add_u64 v[2:3], v[2:3], 0, s[82:83]
	s_mov_b32 m0, s21
	s_add_u32 s8, s2, 0x18080
	global_load_lds_dwordx4 v[2:3], off
	v_lshl_add_u64 v[0:1], v[0:1], 0, s[82:83]
	s_mov_b32 m0, s22
	s_addc_u32 s9, s3, 0
	global_load_lds_dwordx4 v[0:1], off
	s_add_i32 m0, s15, 0x1c000
	v_lshl_add_u64 v[0:1], s[8:9], 0, v[160:161]
	global_load_lds_dwordx4 v[0:1], off
	v_lshl_add_u64 v[0:1], s[8:9], 0, v[128:129]
	s_add_i32 m0, s15, 0x1e000
	s_movk_i32 s8, 0x180
	global_load_lds_dwordx4 v[0:1], off
	s_add_u32 s6, s6, s7
	v_lshrrev_b32_e32 v1, 1, v12
	v_mul_lo_u32 v0, v13, s8
	s_movk_i32 s9, 0x1800
	v_add_lshl_u32 v16, s4, v16, 10
	s_addc_u32 s7, s5, 0
	v_mad_u64_u32 v[0:1], s[4:5], v1, s9, v[0:1]
	v_readlane_b32 s4, v253, 63
	v_readlane_b32 s5, v254, 0
	s_add_u32 s4, s4, s6
	s_addc_u32 s5, s5, s7
	v_or_b32_e32 v0, v0, v14
	s_add_u32 s4, s4, 0x11d18080
	v_add_lshl_u32 v0, v0, v15, 1
	v_mov_b32_e32 v1, v161
	s_addc_u32 s5, s5, 0
	v_lshl_add_u64 v[130:131], s[4:5], 0, v[0:1]
	v_lshrrev_b32_e32 v1, 1, v8
	v_mul_lo_u32 v0, v9, s8
	v_mad_u64_u32 v[0:1], s[6:7], v1, s9, v[0:1]
	v_and_b32_e32 v136, 15, v135
	v_and_b32_e32 v17, 48, v135
	v_lshlrev_b32_e32 v19, 2, v135
	v_or_b32_e32 v0, v0, v10
	v_lshl_or_b32 v17, v136, 6, v17
	v_and_b32_e32 v19, 32, v19
	s_waitcnt vmcnt(6)
	v_add_lshl_u32 v0, v0, v11, 1
	v_mov_b32_e32 v1, v161
	v_bitop3_b32 v18, v17, v18, v19 bitop3:0xde
	v_lshl_add_u64 v[132:133], s[4:5], 0, v[0:1]
	v_mov_b32_e32 v0, 0
	v_bitop3_b32 v137, v16, v17, v19 bitop3:0xf6
	s_mov_b32 s23, -2
	s_mov_b64 s[4:5], 0
	v_add_u32_e32 v138, 0, v18
	v_mov_b32_e32 v1, v0
	v_mov_b32_e32 v2, v0
	v_mov_b32_e32 v3, v0
	v_mov_b32_e32 v4, v0
	v_mov_b32_e32 v5, v0
	v_mov_b32_e32 v6, v0
	v_mov_b32_e32 v7, v0
	v_mov_b32_e32 v16, v0
	v_mov_b32_e32 v17, v0
	v_mov_b32_e32 v18, v0
	v_mov_b32_e32 v19, v0
	v_mov_b32_e32 v20, v0
	v_mov_b32_e32 v21, v0
	v_mov_b32_e32 v22, v0
	v_mov_b32_e32 v23, v0
	v_mov_b32_e32 v32, v0
	v_mov_b32_e32 v33, v0
	v_mov_b32_e32 v34, v0
	v_mov_b32_e32 v35, v0
	v_mov_b32_e32 v36, v0
	v_mov_b32_e32 v37, v0
	v_mov_b32_e32 v38, v0
	v_mov_b32_e32 v39, v0
	v_mov_b32_e32 v48, v0
	v_mov_b32_e32 v49, v0
	v_mov_b32_e32 v50, v0
	v_mov_b32_e32 v51, v0
	v_mov_b32_e32 v52, v0
	v_mov_b32_e32 v53, v0
	v_mov_b32_e32 v54, v0
	v_mov_b32_e32 v55, v0
	v_mov_b32_e32 v8, v0
	v_mov_b32_e32 v9, v0
	v_mov_b32_e32 v10, v0
	v_mov_b32_e32 v11, v0
	v_mov_b32_e32 v12, v0
	v_mov_b32_e32 v13, v0
	v_mov_b32_e32 v14, v0
	v_mov_b32_e32 v15, v0
	v_mov_b32_e32 v24, v0
	v_mov_b32_e32 v25, v0
	v_mov_b32_e32 v26, v0
	v_mov_b32_e32 v27, v0
	v_mov_b32_e32 v28, v0
	v_mov_b32_e32 v29, v0
	v_mov_b32_e32 v30, v0
	v_mov_b32_e32 v31, v0
	v_mov_b32_e32 v40, v0
	v_mov_b32_e32 v41, v0
	v_mov_b32_e32 v42, v0
	v_mov_b32_e32 v43, v0
	v_mov_b32_e32 v44, v0
	v_mov_b32_e32 v45, v0
	v_mov_b32_e32 v46, v0
	v_mov_b32_e32 v47, v0
	v_mov_b32_e32 v56, v0
	v_mov_b32_e32 v57, v0
	v_mov_b32_e32 v58, v0
	v_mov_b32_e32 v59, v0
	v_mov_b32_e32 v60, v0
	v_mov_b32_e32 v61, v0
	v_mov_b32_e32 v62, v0
	v_mov_b32_e32 v63, v0
	v_mov_b32_e32 v64, v0
	v_mov_b32_e32 v65, v0
	v_mov_b32_e32 v66, v0
	v_mov_b32_e32 v67, v0
	v_mov_b32_e32 v68, v0
	v_mov_b32_e32 v69, v0
	v_mov_b32_e32 v70, v0
	v_mov_b32_e32 v71, v0
	v_mov_b32_e32 v80, v0
	v_mov_b32_e32 v81, v0
	v_mov_b32_e32 v82, v0
	v_mov_b32_e32 v83, v0
	v_mov_b32_e32 v84, v0
	v_mov_b32_e32 v85, v0
	v_mov_b32_e32 v86, v0
	v_mov_b32_e32 v87, v0
	v_mov_b32_e32 v96, v0
	v_mov_b32_e32 v97, v0
	v_mov_b32_e32 v98, v0
	v_mov_b32_e32 v99, v0
	v_mov_b32_e32 v100, v0
	v_mov_b32_e32 v101, v0
	v_mov_b32_e32 v102, v0
	v_mov_b32_e32 v103, v0
	v_mov_b32_e32 v112, v0
	v_mov_b32_e32 v113, v0
	v_mov_b32_e32 v114, v0
	v_mov_b32_e32 v115, v0
	v_mov_b32_e32 v116, v0
	v_mov_b32_e32 v117, v0
	v_mov_b32_e32 v118, v0
	v_mov_b32_e32 v119, v0
	v_mov_b32_e32 v72, v0
	v_mov_b32_e32 v73, v0
	v_mov_b32_e32 v74, v0
	v_mov_b32_e32 v75, v0
	v_mov_b32_e32 v76, v0
	v_mov_b32_e32 v77, v0
	v_mov_b32_e32 v78, v0
	v_mov_b32_e32 v79, v0
	v_mov_b32_e32 v88, v0
	v_mov_b32_e32 v89, v0
	v_mov_b32_e32 v90, v0
	v_mov_b32_e32 v91, v0
	v_mov_b32_e32 v92, v0
	v_mov_b32_e32 v93, v0
	v_mov_b32_e32 v94, v0
	v_mov_b32_e32 v95, v0
	v_mov_b32_e32 v104, v0
	v_mov_b32_e32 v105, v0
	v_mov_b32_e32 v106, v0
	v_mov_b32_e32 v107, v0
	v_mov_b32_e32 v108, v0
	v_mov_b32_e32 v109, v0
	v_mov_b32_e32 v110, v0
	v_mov_b32_e32 v111, v0
	v_mov_b32_e32 v120, v0
	v_mov_b32_e32 v121, v0
	v_mov_b32_e32 v122, v0
	v_mov_b32_e32 v123, v0
	v_mov_b32_e32 v124, v0
	v_mov_b32_e32 v125, v0
	v_mov_b32_e32 v126, v0
	v_mov_b32_e32 v127, v0
	s_barrier
	.p2align 6

; template <class Epi, bool ALIGN_EPI>
; __device__ __forceinline__ void gemm_phase(LAS unsigned char* lds, const Gemm g, const Order& S, const Epi& E, const int wave_id) {
;     ...
;         const bool has_next = S.next(ui + 1, nxt);
;         const char* nA = has_next ? (const char*)g.A + (size_t)nxt.z * g.sAz + (size_t)nxt.pm * 2 * hstepA + (size_t)nxt.k0 * 2 : cA;
;         const char* nB = has_next ? (const char*)g.Bt + (size_t)nxt.z * g.sBz + (size_t)nxt.pn * 2 * hstepB + (size_t)nxt.k0 * 2 : cB;
;         const int nt = cur.nt;
;         for (int t = 0; t < nt; t += 2) {
;     ...
;         for (int a = 0; a < 2; ++a)
; #pragma unroll
;             for (int b = 0; b < 2; ++b)
; #pragma unroll
;                 for (int m = 0; m < 4; ++m)
; #pragma unroll
;                     for (int n = 0; n < 2; ++n) acc[a][b][m][n] = (f32x4){0.f, 0.f, 0.f, 0.f};
;         cur = nxt; cA = nA; cB = nB; ++ui;
.LBB0_1152:
	s_ashr_i32 s17, s16, 31
	s_lshl_b64 s[18:19], s[16:17], 17
	s_add_u32 s18, s6, s18
	s_addc_u32 s19, s7, s19
	s_and_b64 s[20:21], s[0:1], exec
	s_cselect_b32 s17, s19, s23
	s_cselect_b32 s59, s18, s22
	s_ashr_i32 s15, s14, 31
	s_lshl_b64 s[20:21], s[14:15], 17
	s_add_u32 s20, s45, s20
	s_addc_u32 s21, s46, s21
	s_and_b64 s[26:27], s[0:1], exec
	v_mov_b32_e32 v0, 0
	s_cselect_b32 s15, s21, s25
	s_cselect_b32 s60, s20, s24
	s_mov_b32 s30, 0
	s_mov_b64 s[26:27], -1
	s_mov_b64 s[28:29], 0
	v_mov_b32_e32 v1, v0
	v_mov_b32_e32 v2, v0
	v_mov_b32_e32 v3, v0
	v_mov_b32_e32 v4, v0
	v_mov_b32_e32 v5, v0
	v_mov_b32_e32 v6, v0
	v_mov_b32_e32 v7, v0
	v_mov_b32_e32 v16, v0
	v_mov_b32_e32 v17, v0
	v_mov_b32_e32 v18, v0
	v_mov_b32_e32 v19, v0
	v_mov_b32_e32 v20, v0
	v_mov_b32_e32 v21, v0
	v_mov_b32_e32 v22, v0
	v_mov_b32_e32 v23, v0
	v_mov_b32_e32 v32, v0
	v_mov_b32_e32 v33, v0
	v_mov_b32_e32 v34, v0
	v_mov_b32_e32 v35, v0
	v_mov_b32_e32 v36, v0
	v_mov_b32_e32 v37, v0
	v_mov_b32_e32 v38, v0
	v_mov_b32_e32 v39, v0
	v_mov_b32_e32 v48, v0
	v_mov_b32_e32 v49, v0
	v_mov_b32_e32 v50, v0
	v_mov_b32_e32 v51, v0
	v_mov_b32_e32 v52, v0
	v_mov_b32_e32 v53, v0
	v_mov_b32_e32 v54, v0
	v_mov_b32_e32 v55, v0
	v_mov_b32_e32 v8, v0
	v_mov_b32_e32 v9, v0
	v_mov_b32_e32 v10, v0
	v_mov_b32_e32 v11, v0
	v_mov_b32_e32 v12, v0
	v_mov_b32_e32 v13, v0
	v_mov_b32_e32 v14, v0
	v_mov_b32_e32 v15, v0
	v_mov_b32_e32 v24, v0
	v_mov_b32_e32 v25, v0
	v_mov_b32_e32 v26, v0
	v_mov_b32_e32 v27, v0
	v_mov_b32_e32 v28, v0
	v_mov_b32_e32 v29, v0
	v_mov_b32_e32 v30, v0
	v_mov_b32_e32 v31, v0
	v_mov_b32_e32 v40, v0
	v_mov_b32_e32 v41, v0
	v_mov_b32_e32 v42, v0
	v_mov_b32_e32 v43, v0
	v_mov_b32_e32 v44, v0
	v_mov_b32_e32 v45, v0
	v_mov_b32_e32 v46, v0
	v_mov_b32_e32 v47, v0
	v_mov_b32_e32 v56, v0
	v_mov_b32_e32 v57, v0
	v_mov_b32_e32 v58, v0
	v_mov_b32_e32 v59, v0
	v_mov_b32_e32 v60, v0
	v_mov_b32_e32 v61, v0
	v_mov_b32_e32 v62, v0
	v_mov_b32_e32 v63, v0
	v_mov_b32_e32 v64, v0
	v_mov_b32_e32 v65, v0
	v_mov_b32_e32 v66, v0
	v_mov_b32_e32 v67, v0
	v_mov_b32_e32 v68, v0
	v_mov_b32_e32 v69, v0
	v_mov_b32_e32 v70, v0
	v_mov_b32_e32 v71, v0
	v_mov_b32_e32 v80, v0
	v_mov_b32_e32 v81, v0
	v_mov_b32_e32 v82, v0
	v_mov_b32_e32 v83, v0
	v_mov_b32_e32 v84, v0
	v_mov_b32_e32 v85, v0
	v_mov_b32_e32 v86, v0
	v_mov_b32_e32 v87, v0
	v_mov_b32_e32 v96, v0
	v_mov_b32_e32 v97, v0
	v_mov_b32_e32 v98, v0
	v_mov_b32_e32 v99, v0
	v_mov_b32_e32 v100, v0
	v_mov_b32_e32 v101, v0
	v_mov_b32_e32 v102, v0
	v_mov_b32_e32 v103, v0
	v_mov_b32_e32 v112, v0
	v_mov_b32_e32 v113, v0
	v_mov_b32_e32 v114, v0
	v_mov_b32_e32 v115, v0
	v_mov_b32_e32 v116, v0
	v_mov_b32_e32 v117, v0
	v_mov_b32_e32 v118, v0
	v_mov_b32_e32 v119, v0
	v_mov_b32_e32 v72, v0
	v_mov_b32_e32 v73, v0
	v_mov_b32_e32 v74, v0
	v_mov_b32_e32 v75, v0
	v_mov_b32_e32 v76, v0
	v_mov_b32_e32 v77, v0
	v_mov_b32_e32 v78, v0
	v_mov_b32_e32 v79, v0
	v_mov_b32_e32 v88, v0
	v_mov_b32_e32 v89, v0
	v_mov_b32_e32 v90, v0
	v_mov_b32_e32 v91, v0
	v_mov_b32_e32 v92, v0
	v_mov_b32_e32 v93, v0
	v_mov_b32_e32 v94, v0
	v_mov_b32_e32 v95, v0
	v_mov_b32_e32 v104, v0
	v_mov_b32_e32 v105, v0
	v_mov_b32_e32 v106, v0
	v_mov_b32_e32 v107, v0
	v_mov_b32_e32 v108, v0
	v_mov_b32_e32 v109, v0
	v_mov_b32_e32 v110, v0
	v_mov_b32_e32 v111, v0
	v_mov_b32_e32 v120, v0
	v_mov_b32_e32 v121, v0
	v_mov_b32_e32 v122, v0
	v_mov_b32_e32 v123, v0
	v_mov_b32_e32 v124, v0
	v_mov_b32_e32 v125, v0
	v_mov_b32_e32 v126, v0
	v_mov_b32_e32 v127, v0
	.p2align 6
